# GEMM phase prologue: the second K-tile's staging loads are issued before the first wait (which leaves them in flight) instead of after its barrier
# baseline (speedup 1.0000x reference)
; #define PG8_STAGE(bufoff, gbase, voff) do { _Pragma("unroll") for (int _i = 0; _i < 2; ++_i) \
;         __builtin_amdgcn_global_load_lds((const unsigned*)((const char*)(gbase) + (voff)[_i]), (PG8_LAS unsigned*)(lds + (bufoff) + ldsw + _i * 8192), 16, 0, 0); } while (0)
; #define PG8_WAIT_V(n) asm volatile("s_waitcnt vmcnt(" #n ")" ::: "memory")
; #define PG8_BAR __builtin_amdgcn_s_barrier()
; template <class Epi, class Sched, bool ALIGN_EPI = false, bool SP2 = false>
; __device__ __forceinline__ void gemm_phase(PG8_LAS unsigned char* lds, const Gemm g, const Sched& S, const Epi& E, const int tid) {
;     const int wid = __builtin_amdgcn_readfirstlane(tid >> 6), lane = tid & 63, wr = wid >> 2, wc = wid & 3, fr = lane & 15, fq = lane >> 4;
;     const int K = g.K, nt = K / BK;
;     unsigned voffA[2], voffB[2];
; #pragma unroll
;     for (int i = 0; i < 2; ++i) { int R, C; stage_rc(tid * 16 + i * 8192, R, C); const int Rb = Epi::PERM ? ((R & ~31) + perm32(R & 31)) : R;
;         voffA[i] = (unsigned)(R * K + C) * 2u; voffB[i] = (unsigned)(Rb * K + C) * 2u; }
;     const size_t kstep = (size_t)(BK * 2);
;     const size_t hstep = (size_t)HALF * K * 2;
;     const size_t tstep = 2 * hstep;
;     const unsigned ldsw = (unsigned)wid * 1024u;
;     const int aoff = lds_byte(wr * 64 + fr, fq * 8), boff = lds_byte(wc * 32 + fr, fq * 8);
;     ...
;     if constexpr (SP2) {
;         PG8_STAGE(PG8_SB(0, 0), cB, voffB); PG8_STAGE(PG8_SB(0, 1), cB + hstep, voffB); PG8_STAGE(PG8_SA(0, 0), cA, voffA); PG8_STAGE(PG8_SA(0, 1), cA + hstep, voffA);
;         if (wr == 1) PG8_BAR;
;         PG8_WAIT_V(2); PG8_BAR;
;         PG8_STAGE(PG8_SB(1, 0), cB + kstep, voffB); PG8_STAGE(PG8_SA(1, 0), cA + kstep, voffA); PG8_STAGE(PG8_SB(1, 1), cB + hstep + kstep, voffB);
;         PG8_WAIT_V(6); PG8_BAR;
.LBB0_56:
	v_readlane_b32 s4, v252, 43
	v_readlane_b32 s5, v252, 44
	v_mov_b32_e32 v147, v1
	v_readlane_b32 s30, v250, 24
	v_lshl_add_u64 v[8:9], s[4:5], 0, v[0:1]
	v_lshl_add_u64 v[10:11], s[4:5], 0, v[146:147]
	v_mov_b32_e32 v151, v1
	v_readlane_b32 s31, v250, 25
	s_add_i32 m0, s33, 0x18000
	v_lshl_add_u64 v[8:9], v[8:9], 0, s[24:25]
	v_lshl_add_u64 v[12:13], s[30:31], 0, v[150:151]
	v_mov_b32_e32 v149, v1
	global_load_lds_dwordx4 v[8:9], off
	v_lshl_add_u64 v[8:9], v[10:11], 0, s[24:25]
	s_add_i32 m0, s33, 0x1a000
	s_add_i32 s7, s33, 0x8000
	v_lshl_add_u64 v[14:15], s[30:31], 0, v[148:149]
	global_load_lds_dwordx4 v[8:9], off
	v_lshl_add_u64 v[8:9], v[12:13], 0, s[24:25]
	s_mov_b32 m0, s7
	s_add_i32 s8, s33, 0xa000
	v_readlane_b32 s10, v252, 45
	global_load_lds_dwordx4 v[8:9], off
	v_lshl_add_u64 v[8:9], v[14:15], 0, s[24:25]
	s_mov_b32 m0, s8
	v_readlane_b32 s11, v252, 46
	global_load_lds_dwordx4 v[8:9], off
	s_add_i32 m0, s33, 0x1c000
	v_lshl_add_u64 v[8:9], s[10:11], 0, v[0:1]
	global_load_lds_dwordx4 v[8:9], off
	v_lshl_add_u64 v[8:9], s[10:11], 0, v[146:147]
	s_add_i32 m0, s33, 0x1e000
	s_and_b32 s1, s1, 3
	global_load_lds_dwordx4 v[8:9], off
	s_waitcnt vmcnt(8)
	s_barrier
	v_bfe_u32 v9, v188, 4, 2
	v_and_b32_e32 v8, 15, v188
	v_lshlrev_b32_e32 v10, 4, v9
	v_lshl_or_b32 v160, s2, 6, v8
	v_lshl_or_b32 v10, v8, 6, v10
	v_lshlrev_b32_e32 v8, 2, v8
	v_lshlrev_b32_e32 v161, 3, v9
	v_and_b32_e32 v11, 32, v8
	v_lshl_or_b32 v8, v9, 6, v8
	v_lshlrev_b32_e32 v9, 14, v6
	s_lshl_b32 s3, s2, 13
	v_and_b32_e32 v9, 0xffff8000, v9
	v_bitop3_b32 v12, v10, s3, v11 bitop3:0xde
	s_lshl_b32 s69, s1, 5
	s_lshl_b32 s3, s1, 12
	v_lshl_add_u32 v5, v5, 11, v9
	v_and_b32_e32 v6, 1, v6
	s_cmpk_lt_u32 s0, 0x100
	v_lshl_or_b32 v5, v6, 6, v5
	s_cselect_b64 s[72:73], -1, 0
	s_or_b32 s0, s1, s2
	v_lshl_add_u32 v154, v7, 1, v5
	v_lshlrev_b32_e32 v5, 14, v2
	s_cmp_lg_u32 s0, 0
	v_readlane_b32 s0, v253, 13
	v_and_b32_e32 v5, 0xffff8000, v5
	v_bitop3_b32 v162, s3, v10, v11 bitop3:0xf6
	s_waitcnt vmcnt(6)
	v_lshlrev_b32_e32 v10, 2, v8
	v_mov_b32_e32 v11, v1
	v_readlane_b32 s1, v253, 14
	v_lshl_add_u32 v3, v3, 11, v5
	v_and_b32_e32 v2, 1, v2
	v_lshl_add_u64 v[152:153], s[0:1], 0, v[10:11]
	v_lshl_or_b32 v2, v2, 6, v3
	v_readlane_b32 s0, v250, 22
	s_mov_b32 s27, 0
	s_cselect_b64 s[74:75], -1, 0
	v_lshlrev_b32_e32 v163, 4, v160
	v_or_b32_e32 v164, s69, v161
	v_mov_b32_e32 v155, v1
	v_lshl_add_u32 v156, v4, 1, v2
	v_mov_b32_e32 v157, v1
	v_add_u32_e32 v165, 0, v12
	v_lshlrev_b32_e32 v166, 2, v8
	v_readlane_b32 s60, v250, 19
	s_mov_b32 s61, s0
	s_movk_i32 s51, 0xb1
	s_movk_i32 s54, 0x1600
	v_readlane_b32 s56, v252, 39
	v_readlane_b32 s57, v252, 40
	v_readlane_b32 s58, v253, 17
	v_readlane_b32 s59, v253, 18
	s_barrier
	v_readlane_b32 s1, v250, 23
	s_branch .LBB0_59

; #define PG8_STAGE(bufoff, gbase, voff) do { _Pragma("unroll") for (int _i = 0; _i < 2; ++_i) \
;         __builtin_amdgcn_global_load_lds((const unsigned*)((const char*)(gbase) + (voff)[_i]), (PG8_LAS unsigned*)(lds + (bufoff) + ldsw + _i * 8192), 16, 0, 0); } while (0)
; #define PG8_WAIT_V(n) asm volatile("s_waitcnt vmcnt(" #n ")" ::: "memory")
; #define PG8_BAR __builtin_amdgcn_s_barrier()
; template <class Epi, class Sched, bool ALIGN_EPI = false, bool SP2 = false>
; __device__ __forceinline__ void gemm_phase(PG8_LAS unsigned char* lds, const Gemm g, const Sched& S, const Epi& E, const int tid) {
;     const int wid = __builtin_amdgcn_readfirstlane(tid >> 6), lane = tid & 63, wr = wid >> 2, wc = wid & 3, fr = lane & 15, fq = lane >> 4;
;     const int K = g.K, nt = K / BK;
;     unsigned voffA[2], voffB[2];
; #pragma unroll
;     for (int i = 0; i < 2; ++i) { int R, C; stage_rc(tid * 16 + i * 8192, R, C); const int Rb = Epi::PERM ? ((R & ~31) + perm32(R & 31)) : R;
;         voffA[i] = (unsigned)(R * K + C) * 2u; voffB[i] = (unsigned)(Rb * K + C) * 2u; }
;     const size_t kstep = (size_t)(BK * 2);
;     const size_t hstep = (size_t)HALF * K * 2;
;     const size_t tstep = 2 * hstep;
;     const unsigned ldsw = (unsigned)wid * 1024u;
;     const int aoff = lds_byte(wr * 64 + fr, fq * 8), boff = lds_byte(wc * 32 + fr, fq * 8);
;     ...
;     if constexpr (SP2) {
;         PG8_STAGE(PG8_SB(0, 0), cB, voffB); PG8_STAGE(PG8_SB(0, 1), cB + hstep, voffB); PG8_STAGE(PG8_SA(0, 0), cA, voffA); PG8_STAGE(PG8_SA(0, 1), cA + hstep, voffA);
;         if (wr == 1) PG8_BAR;
;         PG8_WAIT_V(2); PG8_BAR;
;         PG8_STAGE(PG8_SB(1, 0), cB + kstep, voffB); PG8_STAGE(PG8_SA(1, 0), cA + kstep, voffA); PG8_STAGE(PG8_SB(1, 1), cB + hstep + kstep, voffB);
;         PG8_WAIT_V(6); PG8_BAR;
.LBB0_116:
	v_readlane_b32 s30, v252, 51
	v_readlane_b32 s31, v252, 52
	v_mov_b32_e32 v163, v1
	v_readlane_b32 s36, v250, 36
	v_lshl_add_u64 v[8:9], s[30:31], 0, v[0:1]
	v_lshl_add_u64 v[10:11], s[30:31], 0, v[162:163]
	v_mov_b32_e32 v167, v1
	v_readlane_b32 s37, v250, 37
	s_add_i32 m0, s2, 0x18000
	v_lshl_add_u64 v[8:9], v[8:9], 0, s[24:25]
	v_lshl_add_u64 v[12:13], s[36:37], 0, v[166:167]
	v_mov_b32_e32 v165, v1
	global_load_lds_dwordx4 v[8:9], off
	v_lshl_add_u64 v[8:9], v[10:11], 0, s[24:25]
	s_add_i32 m0, s2, 0x1a000
	s_add_i32 s83, s2, 0x8000
	v_lshl_add_u64 v[14:15], s[36:37], 0, v[164:165]
	global_load_lds_dwordx4 v[8:9], off
	v_lshl_add_u64 v[8:9], v[12:13], 0, s[24:25]
	s_mov_b32 m0, s83
	s_add_i32 s96, s2, 0xa000
	v_readlane_b32 s4, v252, 53
	global_load_lds_dwordx4 v[8:9], off
	v_lshl_add_u64 v[8:9], v[14:15], 0, s[24:25]
	s_mov_b32 m0, s96
	v_readlane_b32 s5, v252, 54
	global_load_lds_dwordx4 v[8:9], off
	s_add_i32 m0, s2, 0x1c000
	v_lshl_add_u64 v[8:9], s[4:5], 0, v[0:1]
	global_load_lds_dwordx4 v[8:9], off
	v_lshl_add_u64 v[8:9], s[4:5], 0, v[162:163]
	s_add_i32 m0, s2, 0x1e000
	v_and_b32_e32 v187, 15, v188
	global_load_lds_dwordx4 v[8:9], off
	s_waitcnt vmcnt(8)
	s_barrier
	v_bfe_u32 v8, v188, 4, 2
	s_lshl_b32 s4, s8, 6
	v_lshlrev_b32_e32 v10, 4, v8
	v_lshlrev_b32_e32 v12, 2, v187
	s_and_b32 s1, s1, 3
	v_writelane_b32 v253, s4, 36
	v_lshl_or_b32 v11, v187, 6, v10
	s_lshl_b32 s4, s8, 13
	v_and_b32_e32 v13, 32, v12
	v_bitop3_b32 v14, v11, s4, v13 bitop3:0xde
	s_lshl_b32 s4, s1, 12
	s_cmpk_lt_u32 s0, 0x100
	v_lshlrev_b32_e32 v9, 3, v8
	v_bitop3_b32 v189, s4, v11, v13 bitop3:0xf6
	s_cselect_b64 s[4:5], -1, 0
	v_lshl_or_b32 v192, s1, 5, v9
	v_writelane_b32 v253, s4, 38
	s_lshl_b32 s9, s1, 10
	s_and_b32 s0, s0, 0xffffff00
	s_lshl_b32 s1, s1, 6
	v_writelane_b32 v253, s5, 39
	v_cmp_eq_u32_e64 s[4:5], 0, v8
	s_or_b32 s0, s1, s0
	v_lshlrev_b32_e32 v8, 14, v6
	v_or3_b32 v193, s0, v10, v187
	s_movk_i32 s0, 0x100
	v_and_b32_e32 v8, 0xffff8000, v8
	v_cmp_gt_i32_e64 s[0:1], s0, v193
	v_lshl_add_u32 v5, v5, 11, v8
	v_and_b32_e32 v6, 1, v6
	v_writelane_b32 v253, s0, 40
	v_readlane_b32 s10, v251, 32
	v_lshl_or_b32 v5, v6, 6, v5
	v_writelane_b32 v253, s1, 41
	s_add_i32 s0, s10, s9
	s_lshl_b32 s1, s8, 8
	v_lshl_add_u32 v168, v7, 1, v5
	v_lshlrev_b32_e32 v5, 14, v2
	s_add_i32 s0, s0, s1
	v_and_b32_e32 v5, 0xffff8000, v5
	s_waitcnt vmcnt(6)
	v_add_u32_e32 v194, s0, v12
	v_lshl_add_u32 v3, v3, 11, v5
	v_and_b32_e32 v2, 1, v2
	v_readlane_b32 s0, v250, 30
	v_lshl_or_b32 v2, v2, 6, v3
	s_mov_b32 s38, s0
	v_readlane_b32 s0, v250, 48
	s_mov_b32 s33, 0
	v_lshl_add_u32 v195, v193, 2, s10
	v_mov_b32_e32 v169, v1
	v_lshl_add_u32 v170, v4, 1, v2
	v_mov_b32_e32 v171, v1
	v_add_u32_e32 v196, 0, v14
	s_mov_b32 s27, s0
	s_barrier
	v_readlane_b32 s1, v250, 49
	s_branch .LBB0_119

; #define PG8_STAGE(bufoff, gbase, voff) do { _Pragma("unroll") for (int _i = 0; _i < 2; ++_i) \
;         __builtin_amdgcn_global_load_lds((const unsigned*)((const char*)(gbase) + (voff)[_i]), (PG8_LAS unsigned*)(lds + (bufoff) + ldsw + _i * 8192), 16, 0, 0); } while (0)
; #define PG8_WAIT_V(n) asm volatile("s_waitcnt vmcnt(" #n ")" ::: "memory")
; #define PG8_BAR __builtin_amdgcn_s_barrier()
; template <class Epi, class Sched, bool ALIGN_EPI = false, bool SP2 = false>
; __device__ __forceinline__ void gemm_phase(PG8_LAS unsigned char* lds, const Gemm g, const Sched& S, const Epi& E, const int tid) {
;     const int wid = __builtin_amdgcn_readfirstlane(tid >> 6), lane = tid & 63, wr = wid >> 2, wc = wid & 3, fr = lane & 15, fq = lane >> 4;
;     const int K = g.K, nt = K / BK;
;     unsigned voffA[2], voffB[2];
; #pragma unroll
;     for (int i = 0; i < 2; ++i) { int R, C; stage_rc(tid * 16 + i * 8192, R, C); const int Rb = Epi::PERM ? ((R & ~31) + perm32(R & 31)) : R;
;         voffA[i] = (unsigned)(R * K + C) * 2u; voffB[i] = (unsigned)(Rb * K + C) * 2u; }
;     const size_t kstep = (size_t)(BK * 2);
;     const size_t hstep = (size_t)HALF * K * 2;
;     const size_t tstep = 2 * hstep;
;     const unsigned ldsw = (unsigned)wid * 1024u;
;     const int aoff = lds_byte(wr * 64 + fr, fq * 8), boff = lds_byte(wc * 32 + fr, fq * 8);
;     ...
;     if constexpr (SP2) {
;         PG8_STAGE(PG8_SB(0, 0), cB, voffB); PG8_STAGE(PG8_SB(0, 1), cB + hstep, voffB); PG8_STAGE(PG8_SA(0, 0), cA, voffA); PG8_STAGE(PG8_SA(0, 1), cA + hstep, voffA);
;         if (wr == 1) PG8_BAR;
;         PG8_WAIT_V(2); PG8_BAR;
;         PG8_STAGE(PG8_SB(1, 0), cB + kstep, voffB); PG8_STAGE(PG8_SA(1, 0), cA + kstep, voffA); PG8_STAGE(PG8_SB(1, 1), cB + hstep + kstep, voffB);
;         PG8_WAIT_V(6); PG8_BAR;
.LBB0_242:
	v_readlane_b32 s36, v253, 3
	v_readlane_b32 s37, v253, 4
	v_mov_b32_e32 v163, v1
	v_readlane_b32 s88, v250, 50
	v_lshl_add_u64 v[10:11], s[36:37], 0, v[0:1]
	v_lshl_add_u64 v[12:13], s[36:37], 0, v[162:163]
	v_mov_b32_e32 v167, v1
	v_readlane_b32 s89, v250, 51
	s_add_i32 m0, s33, 0x18000
	v_lshl_add_u64 v[10:11], v[10:11], 0, s[24:25]
	v_lshl_add_u64 v[14:15], s[88:89], 0, v[166:167]
	v_mov_b32_e32 v165, v1
	global_load_lds_dwordx4 v[10:11], off
	v_lshl_add_u64 v[10:11], v[12:13], 0, s[24:25]
	s_add_i32 m0, s33, 0x1a000
	s_add_i32 s60, s33, 0x8000
	v_lshl_add_u64 v[16:17], s[88:89], 0, v[164:165]
	global_load_lds_dwordx4 v[10:11], off
	v_lshl_add_u64 v[10:11], v[14:15], 0, s[24:25]
	s_mov_b32 m0, s60
	s_add_i32 s61, s33, 0xa000
	v_readlane_b32 s6, v253, 5
	global_load_lds_dwordx4 v[10:11], off
	v_lshl_add_u64 v[10:11], v[16:17], 0, s[24:25]
	s_mov_b32 m0, s61
	v_readlane_b32 s7, v253, 6
	global_load_lds_dwordx4 v[10:11], off
	s_add_i32 m0, s33, 0x1c000
	v_lshl_add_u64 v[10:11], s[6:7], 0, v[0:1]
	global_load_lds_dwordx4 v[10:11], off
	v_lshl_add_u64 v[10:11], s[6:7], 0, v[162:163]
	s_add_i32 m0, s33, 0x1e000
	s_and_b32 s3, s0, 3
	global_load_lds_dwordx4 v[10:11], off
	s_waitcnt vmcnt(8)
	s_barrier
	v_bfe_u32 v10, v188, 4, 2
	v_and_b32_e32 v11, 15, v188
	v_lshlrev_b32_e32 v13, 4, v10
	v_lshlrev_b32_e32 v15, 2, v11
	v_lshl_or_b32 v14, v11, 6, v13
	s_lshl_b32 s0, s4, 13
	v_and_b32_e32 v16, 32, v15
	v_bitop3_b32 v17, v14, s0, v16 bitop3:0xde
	s_lshl_b32 s0, s3, 12
	v_lshlrev_b32_e32 v12, 3, v10
	s_cmpk_lt_u32 s2, 0x100
	v_lshl_or_b32 v190, s3, 5, v12
	s_cselect_b64 s[10:11], -1, 0
	s_lshl_b32 s5, s3, 10
	s_and_b32 s2, s2, 0xffffff00
	s_lshl_b32 s3, s3, 6
	s_or_b32 s2, s3, s2
	v_or3_b32 v191, s2, v13, v11
	v_readlane_b32 s6, v251, 32
	v_lshl_or_b32 v187, s4, 6, v11
	s_add_i32 s5, s6, s5
	s_lshl_b32 s4, s4, 8
	v_lshl_add_u32 v193, v191, 2, s6
	s_movk_i32 s6, 0xb00
	s_add_i32 s5, s5, s4
	v_lshrrev_b32_e32 v7, 1, v7
	v_mul_lo_u32 v6, v6, s6
	s_mov_b32 s7, 0xb000
	v_add_u32_e32 v192, s5, v15
	v_mad_u64_u32 v[6:7], s[4:5], v7, s7, v[6:7]
	v_or_b32_e32 v6, v6, v8
	v_add_lshl_u32 v6, v6, v9, 1
	v_mov_b32_e32 v7, v1
	s_mov_b64 s[30:31], 0xb0080
	v_lshl_add_u64 v[168:169], v[6:7], 0, s[30:31]
	v_lshrrev_b32_e32 v6, 1, v2
	v_mul_lo_u32 v2, v3, s6
	v_mad_u64_u32 v[2:3], s[4:5], v6, s7, v[2:3]
	s_waitcnt vmcnt(6)
	v_or_b32_e32 v2, v2, v4
	v_readlane_b32 s4, v250, 30
	s_movk_i32 s2, 0x100
	v_add_lshl_u32 v2, v2, v5, 1
	v_mov_b32_e32 v3, v1
	s_mov_b32 s38, s4
	v_readlane_b32 s4, v250, 48
	v_readlane_b32 s54, v249, 57
	v_readlane_b32 s72, v252, 27
	v_bitop3_b32 v189, s0, v14, v16 bitop3:0xf6
	s_mov_b32 s62, 0
	v_cmp_eq_u32_e64 s[0:1], 0, v10
	v_cmp_gt_i32_e64 s[2:3], s2, v191
	v_lshl_add_u64 v[170:171], v[2:3], 0, s[30:31]
	v_add_u32_e32 v194, 0, v17
	s_mov_b32 s39, s4
	s_mov_b64 s[30:31], s[36:37]
	v_readlane_b32 s55, v249, 58
	s_mov_b64 s[56:57], 0x20000
	s_mov_b64 s[58:59], 0x28000
	s_mov_b64 s[70:71], 0x2c000
	v_readlane_b32 s73, v252, 28
	v_readlane_b32 s69, v252, 63
	v_readlane_b32 s74, v253, 0
	v_readlane_b32 s75, v252, 31
	s_barrier
	v_readlane_b32 s5, v250, 49
	s_branch .LBB0_245

; #define PG8_STAGE(bufoff, gbase, voff) do { _Pragma("unroll") for (int _i = 0; _i < 2; ++_i) \
;         __builtin_amdgcn_global_load_lds((const unsigned*)((const char*)(gbase) + (voff)[_i]), (PG8_LAS unsigned*)(lds + (bufoff) + ldsw + _i * 8192), 16, 0, 0); } while (0)
; #define PG8_WAIT_V(n) asm volatile("s_waitcnt vmcnt(" #n ")" ::: "memory")
; #define PG8_BAR __builtin_amdgcn_s_barrier()
; template <class Epi, class Sched, bool ALIGN_EPI = false, bool SP2 = false>
; __device__ __forceinline__ void gemm_phase(PG8_LAS unsigned char* lds, const Gemm g, const Sched& S, const Epi& E, const int tid) {
;     const int wid = __builtin_amdgcn_readfirstlane(tid >> 6), lane = tid & 63, wr = wid >> 2, wc = wid & 3, fr = lane & 15, fq = lane >> 4;
;     const int K = g.K, nt = K / BK;
;     unsigned voffA[2], voffB[2];
; #pragma unroll
;     for (int i = 0; i < 2; ++i) { int R, C; stage_rc(tid * 16 + i * 8192, R, C); const int Rb = Epi::PERM ? ((R & ~31) + perm32(R & 31)) : R;
;         voffA[i] = (unsigned)(R * K + C) * 2u; voffB[i] = (unsigned)(Rb * K + C) * 2u; }
;     const size_t kstep = (size_t)(BK * 2);
;     const size_t hstep = (size_t)HALF * K * 2;
;     const size_t tstep = 2 * hstep;
;     const unsigned ldsw = (unsigned)wid * 1024u;
;     const int aoff = lds_byte(wr * 64 + fr, fq * 8), boff = lds_byte(wc * 32 + fr, fq * 8);
;     ...
;     if constexpr (SP2) {
;         PG8_STAGE(PG8_SB(0, 0), cB, voffB); PG8_STAGE(PG8_SB(0, 1), cB + hstep, voffB); PG8_STAGE(PG8_SA(0, 0), cA, voffA); PG8_STAGE(PG8_SA(0, 1), cA + hstep, voffA);
;         if (wr == 1) PG8_BAR;
;         PG8_WAIT_V(2); PG8_BAR;
;         PG8_STAGE(PG8_SB(1, 0), cB + kstep, voffB); PG8_STAGE(PG8_SA(1, 0), cA + kstep, voffA); PG8_STAGE(PG8_SB(1, 1), cB + hstep + kstep, voffB);
;         PG8_WAIT_V(6); PG8_BAR;
.LBB0_392:
	v_readlane_b32 s30, v252, 59
	v_mov_b32_e32 v191, v1
	v_readlane_b32 s31, v252, 60
	v_mov_b32_e32 v179, v1
	v_readlane_b32 s36, v250, 44
	v_lshl_add_u64 v[8:9], s[30:31], 0, v[190:191]
	v_lshl_add_u64 v[10:11], s[30:31], 0, v[178:179]
	v_mov_b32_e32 v193, v1
	v_readlane_b32 s37, v250, 45
	s_add_i32 m0, s27, 0x18000
	v_lshl_add_u64 v[8:9], v[8:9], 0, s[24:25]
	v_lshl_add_u64 v[12:13], s[36:37], 0, v[192:193]
	v_mov_b32_e32 v181, v1
	global_load_lds_dwordx4 v[8:9], off
	v_lshl_add_u64 v[8:9], v[10:11], 0, s[24:25]
	s_add_i32 m0, s27, 0x1a000
	s_add_i32 s62, s27, 0x8000
	v_lshl_add_u64 v[14:15], s[36:37], 0, v[180:181]
	global_load_lds_dwordx4 v[8:9], off
	v_lshl_add_u64 v[8:9], v[12:13], 0, s[24:25]
	s_mov_b32 m0, s62
	s_add_i32 s63, s27, 0xa000
	v_readlane_b32 s4, v252, 61
	global_load_lds_dwordx4 v[8:9], off
	v_lshl_add_u64 v[8:9], v[14:15], 0, s[24:25]
	s_mov_b32 m0, s63
	v_readlane_b32 s5, v252, 62
	global_load_lds_dwordx4 v[8:9], off
	s_add_i32 m0, s27, 0x1c000
	v_lshl_add_u64 v[8:9], s[4:5], 0, v[190:191]
	global_load_lds_dwordx4 v[8:9], off
	v_lshl_add_u64 v[8:9], s[4:5], 0, v[178:179]
	s_add_i32 m0, s27, 0x1e000
	v_and_b32_e32 v0, 15, v188
	global_load_lds_dwordx4 v[8:9], off
	s_waitcnt vmcnt(8)
	s_barrier
	v_bfe_u32 v8, v188, 4, 2
	v_lshlrev_b32_e32 v9, 4, v8
	v_lshl_or_b32 v187, s2, 6, v0
	v_lshl_or_b32 v9, v0, 6, v9
	v_lshlrev_b32_e32 v0, 2, v0
	v_lshlrev_b32_e32 v194, 3, v8
	v_lshl_or_b32 v8, v8, 6, v0
	v_and_b32_e32 v10, 32, v0
	v_lshlrev_b32_e32 v0, 2, v8
	v_lshl_add_u64 v[196:197], s[34:35], 0, v[0:1]
	v_lshlrev_b32_e32 v0, 14, v6
	v_and_b32_e32 v0, 0xffff8000, v0
	s_and_b32 s1, s1, 3
	s_lshl_b32 s3, s2, 13
	v_lshl_add_u32 v0, v5, 11, v0
	v_and_b32_e32 v5, 1, v6
	v_bitop3_b32 v11, v9, s3, v10 bitop3:0xde
	s_lshl_b32 s3, s1, 12
	v_lshl_or_b32 v0, v5, 6, v0
	s_cmpk_lt_u32 s0, 0x100
	v_lshl_add_u32 v198, v7, 1, v0
	v_lshlrev_b32_e32 v0, 14, v2
	s_cselect_b64 s[6:7], -1, 0
	s_or_b32 s0, s1, s2
	v_and_b32_e32 v0, 0xffff8000, v0
	s_waitcnt vmcnt(6)
	s_cmp_lg_u32 s0, 0
	v_lshl_add_u32 v0, v3, 11, v0
	v_and_b32_e32 v2, 1, v2
	s_cselect_b64 s[8:9], -1, 0
	s_lshl_b32 s64, s1, 7
	v_lshl_or_b32 v233, s1, 6, v194
	v_lshl_or_b32 v0, v2, 6, v0
	v_readlane_b32 s0, v250, 42
	v_readlane_b32 s70, v249, 13
	v_bitop3_b32 v189, s3, v9, v10 bitop3:0xf6
	s_mov_b32 s68, 0
	v_lshlrev_b32_e32 v195, 4, v187
	v_mov_b32_e32 v199, v1
	v_lshl_add_u32 v200, v4, 1, v0
	v_mov_b32_e32 v201, v1
	v_add_u32_e32 v234, 0, v11
	v_lshlrev_b32_e32 v235, 2, v8
	v_lshlrev_b32_e32 v0, 2, v194
	v_readlane_b32 s66, v250, 33
	s_mov_b32 s67, s0
	v_readlane_b32 s71, v249, 14
	s_barrier
	v_readlane_b32 s1, v250, 43
	s_branch .LBB0_395
